# v051 + hyconv: next channel's first-stage rows prefetched to L2 from the second Toeplitz ladder
# baseline (speedup 1.0000x reference)
.LBB0_866:
	s_or_b64 exec, exec, s[4:5]
	ds_read_b128 v[14:17], v97 offset:4064
	ds_read_b128 v[18:21], v97 offset:4000
	ds_read_b128 v[46:49], v149
	ds_read_b128 v[42:45], v97 offset:3680
	ds_read_b128 v[74:77], v97 offset:3616
	ds_read_b128 v[26:29], v97 offset:3936
	ds_read_b128 v[30:33], v97 offset:3872
	ds_read_b128 v[34:37], v97 offset:3808
	ds_read_b128 v[38:41], v97 offset:3744
	ds_read_b128 v[22:25], v97 offset:4128
	ds_read_b128 v[78:81], v150
	s_waitcnt lgkmcnt(7)
	v_mfma_f32_16x16x32_bf16 v[82:85], v[42:45], v[46:49], 0
	s_add_i32 s4, s24, 0x1000
	s_mul_hi_i32 s5, s4, 0xc000
	s_mul_i32 s4, s4, 0xc000
	v_mfma_f32_16x16x32_bf16 v[50:53], v[14:17], v[46:49], 0
	s_add_u32 s42, s20, s4
	s_addc_u32 s43, s68, s5
	v_lshlrev_b32_e32 v222, 1, v96
	v_mov_b32_e32 v223, 0
	v_lshl_add_u64 v[222:223], s[42:43], 0, v[222:223]
	v_lshl_add_u64 v[222:223], v[98:99], 1, v[222:223]
	v_lshl_add_u64 v[222:223], v[222:223], 0, s[16:17]
	global_load_dword v224, v[222:223], off
	global_load_dword v224, v[222:223], off offset:64
	global_load_dword v224, v[222:223], off offset:128
	global_load_dword v224, v[222:223], off offset:192
	global_load_dword v224, v[222:223], off offset:256
	global_load_dword v224, v[222:223], off offset:320
	global_load_dword v224, v[222:223], off offset:384
	global_load_dword v224, v[222:223], off offset:448
	s_sub_i32 s101, s24, s100
	s_mul_hi_i32 s99, s101, 0x6000
	s_mul_i32 s98, s101, 0x6000
	s_lshl_b64 s[98:99], s[98:99], 1
	s_add_u32 s98, s20, s98
	s_addc_u32 s99, s68, s99
	v_lshl_add_u64 v[222:223], s[98:99], 0, v[130:131]
	v_lshl_add_u64 v[222:223], v[222:223], 0, s[16:17]
	v_lshl_add_u64 v[228:229], v[88:89], 1, v[222:223]
	global_load_dword v230, v[228:229], off
	v_lshl_add_u64 v[228:229], v[90:91], 1, v[222:223]
	global_load_dword v230, v[228:229], off
	v_lshl_add_u64 v[228:229], v[92:93], 1, v[222:223]
	global_load_dword v230, v[228:229], off
	v_lshl_add_u64 v[228:229], v[94:95], 1, v[222:223]
	global_load_dword v230, v[228:229], off
	v_mov_b32_e32 v135, v131
	v_mfma_f32_16x16x32_bf16 v[54:57], v[18:21], v[46:49], 0
	s_waitcnt lgkmcnt(5)
	v_mfma_f32_16x16x32_bf16 v[58:61], v[26:29], v[46:49], 0
	s_waitcnt lgkmcnt(4)
	v_mfma_f32_16x16x32_bf16 v[62:65], v[30:33], v[46:49], 0
	s_waitcnt lgkmcnt(3)
	v_mfma_f32_16x16x32_bf16 v[66:69], v[34:37], v[46:49], 0
	s_waitcnt lgkmcnt(2)
	v_mfma_f32_16x16x32_bf16 v[70:73], v[38:41], v[46:49], 0
	v_mfma_f32_16x16x32_bf16 v[46:49], v[74:77], v[46:49], 0
	s_waitcnt lgkmcnt(0)
	v_mfma_f32_16x16x32_bf16 v[74:77], v[38:41], v[78:81], v[82:85]
	s_nop 2
	ds_read_b128 v[82:85], v97 offset:4192
	v_mfma_f32_16x16x32_bf16 v[42:45], v[42:45], v[78:81], v[46:49]
	s_nop 2
	ds_read_b128 v[46:49], v150 offset:64
	v_mfma_f32_16x16x32_bf16 v[50:53], v[22:25], v[78:81], v[50:53]
	v_mfma_f32_16x16x32_bf16 v[54:57], v[14:17], v[78:81], v[54:57]
	v_mfma_f32_16x16x32_bf16 v[58:61], v[18:21], v[78:81], v[58:61]
	v_mfma_f32_16x16x32_bf16 v[62:65], v[26:29], v[78:81], v[62:65]
	v_mfma_f32_16x16x32_bf16 v[66:69], v[30:33], v[78:81], v[66:69]
	v_mfma_f32_16x16x32_bf16 v[70:73], v[34:37], v[78:81], v[70:73]
	ds_read_b128 v[78:81], v97 offset:4256
	s_waitcnt lgkmcnt(1)
	v_mfma_f32_16x16x32_bf16 v[38:41], v[38:41], v[46:49], v[42:45]
	s_nop 2
	ds_read_b128 v[42:45], v150 offset:128
	v_mfma_f32_16x16x32_bf16 v[50:53], v[82:85], v[46:49], v[50:53]
	v_mfma_f32_16x16x32_bf16 v[54:57], v[22:25], v[46:49], v[54:57]
	v_mfma_f32_16x16x32_bf16 v[58:61], v[14:17], v[46:49], v[58:61]
	v_mfma_f32_16x16x32_bf16 v[62:65], v[18:21], v[46:49], v[62:65]
	v_mfma_f32_16x16x32_bf16 v[66:69], v[26:29], v[46:49], v[66:69]
	v_mfma_f32_16x16x32_bf16 v[70:73], v[30:33], v[46:49], v[70:73]
	v_mfma_f32_16x16x32_bf16 v[74:77], v[34:37], v[46:49], v[74:77]
	s_waitcnt lgkmcnt(0)
	v_mfma_f32_16x16x32_bf16 v[46:49], v[78:81], v[42:45], v[50:53]
	v_mfma_f32_16x16x32_bf16 v[50:53], v[82:85], v[42:45], v[54:57]
	v_mfma_f32_16x16x32_bf16 v[54:57], v[22:25], v[42:45], v[58:61]
	v_mfma_f32_16x16x32_bf16 v[58:61], v[14:17], v[42:45], v[62:65]
	v_mfma_f32_16x16x32_bf16 v[62:65], v[18:21], v[42:45], v[66:69]
	v_mfma_f32_16x16x32_bf16 v[66:69], v[26:29], v[42:45], v[70:73]
	v_mfma_f32_16x16x32_bf16 v[70:73], v[30:33], v[42:45], v[74:77]
	s_nop 2
	ds_read_b128 v[74:77], v97 offset:4320
	v_mfma_f32_16x16x32_bf16 v[34:37], v[34:37], v[42:45], v[38:41]
	s_nop 2
	ds_read_b128 v[38:41], v150 offset:192
	s_waitcnt lgkmcnt(0)
	v_mfma_f32_16x16x32_bf16 v[42:45], v[74:77], v[38:41], v[46:49]
	v_mfma_f32_16x16x32_bf16 v[46:49], v[78:81], v[38:41], v[50:53]
	v_mfma_f32_16x16x32_bf16 v[50:53], v[82:85], v[38:41], v[54:57]
	v_mfma_f32_16x16x32_bf16 v[54:57], v[22:25], v[38:41], v[58:61]
	v_mfma_f32_16x16x32_bf16 v[58:61], v[14:17], v[38:41], v[62:65]
	v_mfma_f32_16x16x32_bf16 v[62:65], v[18:21], v[38:41], v[66:69]
	v_mfma_f32_16x16x32_bf16 v[66:69], v[26:29], v[38:41], v[70:73]
	s_nop 2
	ds_read_b128 v[70:73], v97 offset:4384
	v_mfma_f32_16x16x32_bf16 v[30:33], v[30:33], v[38:41], v[34:37]
	s_nop 2
	ds_read_b128 v[34:37], v150 offset:256
	s_waitcnt lgkmcnt(0)
	v_mfma_f32_16x16x32_bf16 v[38:41], v[70:73], v[34:37], v[42:45]
	v_mfma_f32_16x16x32_bf16 v[42:45], v[74:77], v[34:37], v[46:49]
	v_mfma_f32_16x16x32_bf16 v[46:49], v[78:81], v[34:37], v[50:53]
	v_mfma_f32_16x16x32_bf16 v[50:53], v[82:85], v[34:37], v[54:57]
	v_mfma_f32_16x16x32_bf16 v[54:57], v[22:25], v[34:37], v[58:61]
	v_mfma_f32_16x16x32_bf16 v[58:61], v[14:17], v[34:37], v[62:65]
	v_mfma_f32_16x16x32_bf16 v[62:65], v[18:21], v[34:37], v[66:69]
	s_nop 2
	ds_read_b128 v[66:69], v97 offset:4448
	v_mfma_f32_16x16x32_bf16 v[26:29], v[26:29], v[34:37], v[30:33]
	s_nop 2
	ds_read_b128 v[30:33], v150 offset:320
	s_waitcnt lgkmcnt(0)
	v_mfma_f32_16x16x32_bf16 v[34:37], v[66:69], v[30:33], v[38:41]
	v_mfma_f32_16x16x32_bf16 v[38:41], v[70:73], v[30:33], v[42:45]
	v_mfma_f32_16x16x32_bf16 v[42:45], v[74:77], v[30:33], v[46:49]
	v_mfma_f32_16x16x32_bf16 v[46:49], v[78:81], v[30:33], v[50:53]
	v_mfma_f32_16x16x32_bf16 v[50:53], v[82:85], v[30:33], v[54:57]
	v_mfma_f32_16x16x32_bf16 v[54:57], v[22:25], v[30:33], v[58:61]
	v_mfma_f32_16x16x32_bf16 v[58:61], v[14:17], v[30:33], v[62:65]
	s_nop 2
	ds_read_b128 v[62:65], v97 offset:4512
	v_mfma_f32_16x16x32_bf16 v[18:21], v[18:21], v[30:33], v[26:29]
	s_nop 2
	ds_read_b128 v[26:29], v150 offset:384
	s_waitcnt lgkmcnt(0)
	v_mfma_f32_16x16x32_bf16 v[30:33], v[62:65], v[26:29], v[34:37]
	v_mfma_f32_16x16x32_bf16 v[34:37], v[66:69], v[26:29], v[38:41]
	v_mfma_f32_16x16x32_bf16 v[38:41], v[70:73], v[26:29], v[42:45]
	v_mfma_f32_16x16x32_bf16 v[42:45], v[74:77], v[26:29], v[46:49]
	v_mfma_f32_16x16x32_bf16 v[46:49], v[78:81], v[26:29], v[50:53]
	v_mfma_f32_16x16x32_bf16 v[50:53], v[82:85], v[26:29], v[54:57]
	v_mfma_f32_16x16x32_bf16 v[54:57], v[22:25], v[26:29], v[58:61]
	s_nop 2
	ds_read_b128 v[58:61], v97 offset:4576
	v_mfma_f32_16x16x32_bf16 v[14:17], v[14:17], v[26:29], v[18:21]
	s_nop 2
	ds_read_b128 v[18:21], v150 offset:448
	s_waitcnt lgkmcnt(0)
	v_mfma_f32_16x16x32_bf16 v[26:29], v[58:61], v[18:21], v[30:33]
	v_mfma_f32_16x16x32_bf16 v[30:33], v[62:65], v[18:21], v[34:37]
	v_mfma_f32_16x16x32_bf16 v[34:37], v[66:69], v[18:21], v[38:41]
	v_mfma_f32_16x16x32_bf16 v[38:41], v[70:73], v[18:21], v[42:45]
	v_mfma_f32_16x16x32_bf16 v[42:45], v[74:77], v[18:21], v[46:49]
	v_mfma_f32_16x16x32_bf16 v[46:49], v[78:81], v[18:21], v[50:53]
	v_mfma_f32_16x16x32_bf16 v[50:53], v[82:85], v[18:21], v[54:57]
	s_nop 2
	ds_read_b128 v[54:57], v97 offset:4640
	v_mfma_f32_16x16x32_bf16 v[14:17], v[22:25], v[18:21], v[14:17]
	ds_read_b128 v[18:21], v150 offset:512
	s_waitcnt lgkmcnt(0)
	v_mfma_f32_16x16x32_bf16 v[14:17], v[82:85], v[18:21], v[14:17]
	ds_read_b128 v[82:85], v97 offset:4768
	v_mfma_f32_16x16x32_bf16 v[22:25], v[54:57], v[18:21], v[26:29]
	v_mfma_f32_16x16x32_bf16 v[26:29], v[58:61], v[18:21], v[30:33]
	v_mfma_f32_16x16x32_bf16 v[30:33], v[62:65], v[18:21], v[34:37]
	v_mfma_f32_16x16x32_bf16 v[34:37], v[66:69], v[18:21], v[38:41]
	v_mfma_f32_16x16x32_bf16 v[38:41], v[70:73], v[18:21], v[42:45]
	v_mfma_f32_16x16x32_bf16 v[42:45], v[74:77], v[18:21], v[46:49]
	v_mfma_f32_16x16x32_bf16 v[46:49], v[78:81], v[18:21], v[50:53]
	ds_read_b128 v[18:21], v150 offset:576
	s_nop 1
	ds_read_b128 v[50:53], v97 offset:4704
	s_waitcnt lgkmcnt(1)
	v_mfma_f32_16x16x32_bf16 v[26:29], v[54:57], v[18:21], v[26:29]
	v_mfma_f32_16x16x32_bf16 v[30:33], v[58:61], v[18:21], v[30:33]
	v_mfma_f32_16x16x32_bf16 v[34:37], v[62:65], v[18:21], v[34:37]
	v_mfma_f32_16x16x32_bf16 v[38:41], v[66:69], v[18:21], v[38:41]
	v_mfma_f32_16x16x32_bf16 v[42:45], v[70:73], v[18:21], v[42:45]
	v_mfma_f32_16x16x32_bf16 v[46:49], v[74:77], v[18:21], v[46:49]
	v_mfma_f32_16x16x32_bf16 v[14:17], v[78:81], v[18:21], v[14:17]
	ds_read_b128 v[78:81], v97 offset:4832
	s_waitcnt lgkmcnt(1)
	v_mfma_f32_16x16x32_bf16 v[22:25], v[50:53], v[18:21], v[22:25]
	ds_read_b128 v[18:21], v150 offset:640
	s_waitcnt lgkmcnt(0)
	v_mfma_f32_16x16x32_bf16 v[22:25], v[82:85], v[18:21], v[22:25]
	v_mfma_f32_16x16x32_bf16 v[26:29], v[50:53], v[18:21], v[26:29]
	v_mfma_f32_16x16x32_bf16 v[30:33], v[54:57], v[18:21], v[30:33]
	v_mfma_f32_16x16x32_bf16 v[34:37], v[58:61], v[18:21], v[34:37]
	v_mfma_f32_16x16x32_bf16 v[38:41], v[62:65], v[18:21], v[38:41]
	v_mfma_f32_16x16x32_bf16 v[42:45], v[66:69], v[18:21], v[42:45]
	v_mfma_f32_16x16x32_bf16 v[46:49], v[70:73], v[18:21], v[46:49]
	v_mfma_f32_16x16x32_bf16 v[14:17], v[74:77], v[18:21], v[14:17]
	ds_read_b128 v[18:21], v150 offset:704
	ds_read_b128 v[74:77], v97 offset:4896
	s_waitcnt lgkmcnt(1)
	v_mfma_f32_16x16x32_bf16 v[22:25], v[78:81], v[18:21], v[22:25]
	v_mfma_f32_16x16x32_bf16 v[26:29], v[82:85], v[18:21], v[26:29]
	v_mfma_f32_16x16x32_bf16 v[30:33], v[50:53], v[18:21], v[30:33]
	v_mfma_f32_16x16x32_bf16 v[34:37], v[54:57], v[18:21], v[34:37]
	v_mfma_f32_16x16x32_bf16 v[38:41], v[58:61], v[18:21], v[38:41]
	v_mfma_f32_16x16x32_bf16 v[42:45], v[62:65], v[18:21], v[42:45]
	v_mfma_f32_16x16x32_bf16 v[46:49], v[66:69], v[18:21], v[46:49]
	v_mfma_f32_16x16x32_bf16 v[14:17], v[70:73], v[18:21], v[14:17]
	ds_read_b128 v[18:21], v150 offset:768
	ds_read_b128 v[70:73], v97 offset:4960
	s_waitcnt lgkmcnt(1)
	v_mfma_f32_16x16x32_bf16 v[22:25], v[74:77], v[18:21], v[22:25]
	v_mfma_f32_16x16x32_bf16 v[26:29], v[78:81], v[18:21], v[26:29]
	v_mfma_f32_16x16x32_bf16 v[30:33], v[82:85], v[18:21], v[30:33]
	v_mfma_f32_16x16x32_bf16 v[34:37], v[50:53], v[18:21], v[34:37]
	v_mfma_f32_16x16x32_bf16 v[38:41], v[54:57], v[18:21], v[38:41]
	v_mfma_f32_16x16x32_bf16 v[42:45], v[58:61], v[18:21], v[42:45]
	v_mfma_f32_16x16x32_bf16 v[46:49], v[62:65], v[18:21], v[46:49]
	v_mfma_f32_16x16x32_bf16 v[14:17], v[66:69], v[18:21], v[14:17]
	ds_read_b128 v[18:21], v150 offset:832
	ds_read_b128 v[66:69], v97 offset:5024
	s_waitcnt lgkmcnt(1)
	v_mfma_f32_16x16x32_bf16 v[22:25], v[70:73], v[18:21], v[22:25]
	v_mfma_f32_16x16x32_bf16 v[26:29], v[74:77], v[18:21], v[26:29]
	v_mfma_f32_16x16x32_bf16 v[30:33], v[78:81], v[18:21], v[30:33]
	v_mfma_f32_16x16x32_bf16 v[34:37], v[82:85], v[18:21], v[34:37]
	v_mfma_f32_16x16x32_bf16 v[38:41], v[50:53], v[18:21], v[38:41]
	v_mfma_f32_16x16x32_bf16 v[42:45], v[54:57], v[18:21], v[42:45]
	v_mfma_f32_16x16x32_bf16 v[46:49], v[58:61], v[18:21], v[46:49]
	v_mfma_f32_16x16x32_bf16 v[14:17], v[62:65], v[18:21], v[14:17]
	ds_read_b128 v[18:21], v150 offset:896
	ds_read_b128 v[62:65], v97 offset:5088
	s_waitcnt lgkmcnt(1)
	v_mfma_f32_16x16x32_bf16 v[22:25], v[66:69], v[18:21], v[22:25]
	v_mfma_f32_16x16x32_bf16 v[26:29], v[70:73], v[18:21], v[26:29]
	v_mfma_f32_16x16x32_bf16 v[30:33], v[74:77], v[18:21], v[30:33]
	v_mfma_f32_16x16x32_bf16 v[34:37], v[78:81], v[18:21], v[34:37]
	v_mfma_f32_16x16x32_bf16 v[38:41], v[82:85], v[18:21], v[38:41]
	v_mfma_f32_16x16x32_bf16 v[42:45], v[50:53], v[18:21], v[42:45]
	v_mfma_f32_16x16x32_bf16 v[46:49], v[54:57], v[18:21], v[46:49]
	v_mfma_f32_16x16x32_bf16 v[14:17], v[58:61], v[18:21], v[14:17]
	ds_read_b128 v[18:21], v150 offset:960
	ds_read_b128 v[58:61], v97 offset:5152
	s_waitcnt lgkmcnt(1)
	v_mfma_f32_16x16x32_bf16 v[22:25], v[62:65], v[18:21], v[22:25]
	v_mfma_f32_16x16x32_bf16 v[26:29], v[66:69], v[18:21], v[26:29]
	v_mfma_f32_16x16x32_bf16 v[30:33], v[70:73], v[18:21], v[30:33]
	v_mfma_f32_16x16x32_bf16 v[34:37], v[74:77], v[18:21], v[34:37]
	v_mfma_f32_16x16x32_bf16 v[38:41], v[78:81], v[18:21], v[38:41]
	v_mfma_f32_16x16x32_bf16 v[42:45], v[82:85], v[18:21], v[42:45]
	v_mfma_f32_16x16x32_bf16 v[46:49], v[50:53], v[18:21], v[46:49]
	v_mfma_f32_16x16x32_bf16 v[14:17], v[54:57], v[18:21], v[14:17]
	ds_read_b128 v[18:21], v150 offset:1024
	ds_read_b128 v[54:57], v97 offset:5216
	s_waitcnt lgkmcnt(1)
	v_mfma_f32_16x16x32_bf16 v[22:25], v[58:61], v[18:21], v[22:25]
	v_mfma_f32_16x16x32_bf16 v[26:29], v[62:65], v[18:21], v[26:29]
	v_mfma_f32_16x16x32_bf16 v[30:33], v[66:69], v[18:21], v[30:33]
	v_mfma_f32_16x16x32_bf16 v[34:37], v[70:73], v[18:21], v[34:37]
	v_mfma_f32_16x16x32_bf16 v[38:41], v[74:77], v[18:21], v[38:41]
	v_mfma_f32_16x16x32_bf16 v[42:45], v[78:81], v[18:21], v[42:45]
	v_mfma_f32_16x16x32_bf16 v[46:49], v[82:85], v[18:21], v[46:49]
	v_mfma_f32_16x16x32_bf16 v[14:17], v[50:53], v[18:21], v[14:17]
	ds_read_b128 v[18:21], v150 offset:1088
	ds_read_b128 v[50:53], v97 offset:5280
	s_waitcnt lgkmcnt(1)
	v_mfma_f32_16x16x32_bf16 v[22:25], v[54:57], v[18:21], v[22:25]
	v_mfma_f32_16x16x32_bf16 v[26:29], v[58:61], v[18:21], v[26:29]
	v_mfma_f32_16x16x32_bf16 v[30:33], v[62:65], v[18:21], v[30:33]
	v_mfma_f32_16x16x32_bf16 v[34:37], v[66:69], v[18:21], v[34:37]
	v_mfma_f32_16x16x32_bf16 v[38:41], v[70:73], v[18:21], v[38:41]
	v_mfma_f32_16x16x32_bf16 v[42:45], v[74:77], v[18:21], v[42:45]
	v_mfma_f32_16x16x32_bf16 v[46:49], v[78:81], v[18:21], v[46:49]
	v_mfma_f32_16x16x32_bf16 v[14:17], v[82:85], v[18:21], v[14:17]
	ds_read_b128 v[18:21], v150 offset:1152
	ds_read_b128 v[82:85], v97 offset:5344
	s_waitcnt lgkmcnt(1)
	v_mfma_f32_16x16x32_bf16 v[22:25], v[50:53], v[18:21], v[22:25]
	v_mfma_f32_16x16x32_bf16 v[26:29], v[54:57], v[18:21], v[26:29]
	v_mfma_f32_16x16x32_bf16 v[30:33], v[58:61], v[18:21], v[30:33]
	v_mfma_f32_16x16x32_bf16 v[34:37], v[62:65], v[18:21], v[34:37]
	v_mfma_f32_16x16x32_bf16 v[38:41], v[66:69], v[18:21], v[38:41]
	v_mfma_f32_16x16x32_bf16 v[42:45], v[70:73], v[18:21], v[42:45]
	v_mfma_f32_16x16x32_bf16 v[46:49], v[74:77], v[18:21], v[46:49]
	v_mfma_f32_16x16x32_bf16 v[14:17], v[78:81], v[18:21], v[14:17]
	ds_read_b128 v[18:21], v150 offset:1216
	ds_read_b128 v[78:81], v97 offset:5408
	s_waitcnt lgkmcnt(1)
	v_mfma_f32_16x16x32_bf16 v[22:25], v[82:85], v[18:21], v[22:25]
	v_mfma_f32_16x16x32_bf16 v[26:29], v[50:53], v[18:21], v[26:29]
	v_mfma_f32_16x16x32_bf16 v[30:33], v[54:57], v[18:21], v[30:33]
	v_mfma_f32_16x16x32_bf16 v[34:37], v[58:61], v[18:21], v[34:37]
	v_mfma_f32_16x16x32_bf16 v[38:41], v[62:65], v[18:21], v[38:41]
	v_mfma_f32_16x16x32_bf16 v[42:45], v[66:69], v[18:21], v[42:45]
	v_mfma_f32_16x16x32_bf16 v[46:49], v[70:73], v[18:21], v[46:49]
	v_mfma_f32_16x16x32_bf16 v[14:17], v[74:77], v[18:21], v[14:17]
	ds_read_b128 v[18:21], v150 offset:1280
	ds_read_b128 v[74:77], v97 offset:5472
	s_waitcnt lgkmcnt(1)
	v_mfma_f32_16x16x32_bf16 v[22:25], v[78:81], v[18:21], v[22:25]
	v_mfma_f32_16x16x32_bf16 v[26:29], v[82:85], v[18:21], v[26:29]
	v_mfma_f32_16x16x32_bf16 v[30:33], v[50:53], v[18:21], v[30:33]
	v_mfma_f32_16x16x32_bf16 v[34:37], v[54:57], v[18:21], v[34:37]
	v_mfma_f32_16x16x32_bf16 v[38:41], v[58:61], v[18:21], v[38:41]
	v_mfma_f32_16x16x32_bf16 v[42:45], v[62:65], v[18:21], v[42:45]
	v_mfma_f32_16x16x32_bf16 v[46:49], v[66:69], v[18:21], v[46:49]
	v_mfma_f32_16x16x32_bf16 v[14:17], v[70:73], v[18:21], v[14:17]
	ds_read_b128 v[18:21], v150 offset:1344
	ds_read_b128 v[70:73], v97 offset:5536
	s_waitcnt lgkmcnt(1)
	v_mfma_f32_16x16x32_bf16 v[22:25], v[74:77], v[18:21], v[22:25]
	v_mfma_f32_16x16x32_bf16 v[26:29], v[78:81], v[18:21], v[26:29]
	v_mfma_f32_16x16x32_bf16 v[30:33], v[82:85], v[18:21], v[30:33]
	v_mfma_f32_16x16x32_bf16 v[34:37], v[50:53], v[18:21], v[34:37]
	v_mfma_f32_16x16x32_bf16 v[38:41], v[54:57], v[18:21], v[38:41]
	v_mfma_f32_16x16x32_bf16 v[42:45], v[58:61], v[18:21], v[42:45]
	v_mfma_f32_16x16x32_bf16 v[46:49], v[62:65], v[18:21], v[46:49]
	v_mfma_f32_16x16x32_bf16 v[14:17], v[66:69], v[18:21], v[14:17]
	ds_read_b128 v[18:21], v150 offset:1408
	ds_read_b128 v[66:69], v97 offset:5600
	s_waitcnt lgkmcnt(1)
	v_mfma_f32_16x16x32_bf16 v[22:25], v[70:73], v[18:21], v[22:25]
	v_mfma_f32_16x16x32_bf16 v[26:29], v[74:77], v[18:21], v[26:29]
	v_mfma_f32_16x16x32_bf16 v[30:33], v[78:81], v[18:21], v[30:33]
	v_mfma_f32_16x16x32_bf16 v[34:37], v[82:85], v[18:21], v[34:37]
	v_mfma_f32_16x16x32_bf16 v[38:41], v[50:53], v[18:21], v[38:41]
	v_mfma_f32_16x16x32_bf16 v[42:45], v[54:57], v[18:21], v[42:45]
	v_mfma_f32_16x16x32_bf16 v[46:49], v[58:61], v[18:21], v[46:49]
	v_mfma_f32_16x16x32_bf16 v[14:17], v[62:65], v[18:21], v[14:17]
	ds_read_b128 v[18:21], v150 offset:1472
	ds_read_b128 v[62:65], v97 offset:5664
	s_waitcnt lgkmcnt(1)
	v_mfma_f32_16x16x32_bf16 v[22:25], v[66:69], v[18:21], v[22:25]
	v_mfma_f32_16x16x32_bf16 v[26:29], v[70:73], v[18:21], v[26:29]
	v_mfma_f32_16x16x32_bf16 v[30:33], v[74:77], v[18:21], v[30:33]
	v_mfma_f32_16x16x32_bf16 v[34:37], v[78:81], v[18:21], v[34:37]
	v_mfma_f32_16x16x32_bf16 v[38:41], v[82:85], v[18:21], v[38:41]
	v_mfma_f32_16x16x32_bf16 v[42:45], v[50:53], v[18:21], v[42:45]
	v_mfma_f32_16x16x32_bf16 v[46:49], v[54:57], v[18:21], v[46:49]
	v_mfma_f32_16x16x32_bf16 v[14:17], v[58:61], v[18:21], v[14:17]
	ds_read_b128 v[18:21], v150 offset:1536
	ds_read_b128 v[58:61], v97 offset:5728
	s_waitcnt lgkmcnt(1)
	v_mfma_f32_16x16x32_bf16 v[22:25], v[62:65], v[18:21], v[22:25]
	v_mfma_f32_16x16x32_bf16 v[26:29], v[66:69], v[18:21], v[26:29]
	v_mfma_f32_16x16x32_bf16 v[30:33], v[70:73], v[18:21], v[30:33]
	v_mfma_f32_16x16x32_bf16 v[34:37], v[74:77], v[18:21], v[34:37]
	v_mfma_f32_16x16x32_bf16 v[38:41], v[78:81], v[18:21], v[38:41]
	v_mfma_f32_16x16x32_bf16 v[42:45], v[82:85], v[18:21], v[42:45]
	v_mfma_f32_16x16x32_bf16 v[46:49], v[50:53], v[18:21], v[46:49]
	v_mfma_f32_16x16x32_bf16 v[14:17], v[54:57], v[18:21], v[14:17]
	ds_read_b128 v[18:21], v150 offset:1600
	ds_read_b128 v[54:57], v97 offset:5792
	s_waitcnt lgkmcnt(1)
	v_mfma_f32_16x16x32_bf16 v[22:25], v[58:61], v[18:21], v[22:25]
	v_mfma_f32_16x16x32_bf16 v[26:29], v[62:65], v[18:21], v[26:29]
	v_mfma_f32_16x16x32_bf16 v[30:33], v[66:69], v[18:21], v[30:33]
	v_mfma_f32_16x16x32_bf16 v[34:37], v[70:73], v[18:21], v[34:37]
	v_mfma_f32_16x16x32_bf16 v[38:41], v[74:77], v[18:21], v[38:41]
	v_mfma_f32_16x16x32_bf16 v[42:45], v[78:81], v[18:21], v[42:45]
	v_mfma_f32_16x16x32_bf16 v[46:49], v[82:85], v[18:21], v[46:49]
	v_mfma_f32_16x16x32_bf16 v[14:17], v[50:53], v[18:21], v[14:17]
	ds_read_b128 v[18:21], v150 offset:1664
	ds_read_b128 v[50:53], v97 offset:5856
	s_waitcnt lgkmcnt(1)
	v_mfma_f32_16x16x32_bf16 v[22:25], v[54:57], v[18:21], v[22:25]
	v_mfma_f32_16x16x32_bf16 v[26:29], v[58:61], v[18:21], v[26:29]
	v_mfma_f32_16x16x32_bf16 v[30:33], v[62:65], v[18:21], v[30:33]
	v_mfma_f32_16x16x32_bf16 v[34:37], v[66:69], v[18:21], v[34:37]
	v_mfma_f32_16x16x32_bf16 v[38:41], v[70:73], v[18:21], v[38:41]
	v_mfma_f32_16x16x32_bf16 v[42:45], v[74:77], v[18:21], v[42:45]
	v_mfma_f32_16x16x32_bf16 v[46:49], v[78:81], v[18:21], v[46:49]
	v_mfma_f32_16x16x32_bf16 v[14:17], v[82:85], v[18:21], v[14:17]
	ds_read_b128 v[18:21], v150 offset:1728
	ds_read_b128 v[82:85], v97 offset:5920
	s_waitcnt lgkmcnt(1)
	v_mfma_f32_16x16x32_bf16 v[22:25], v[50:53], v[18:21], v[22:25]
	v_mfma_f32_16x16x32_bf16 v[26:29], v[54:57], v[18:21], v[26:29]
	v_mfma_f32_16x16x32_bf16 v[30:33], v[58:61], v[18:21], v[30:33]
	v_mfma_f32_16x16x32_bf16 v[34:37], v[62:65], v[18:21], v[34:37]
	v_mfma_f32_16x16x32_bf16 v[38:41], v[66:69], v[18:21], v[38:41]
	v_mfma_f32_16x16x32_bf16 v[42:45], v[70:73], v[18:21], v[42:45]
	v_mfma_f32_16x16x32_bf16 v[46:49], v[74:77], v[18:21], v[46:49]
	v_mfma_f32_16x16x32_bf16 v[14:17], v[78:81], v[18:21], v[14:17]
	ds_read_b128 v[18:21], v150 offset:1792
	ds_read_b128 v[78:81], v97 offset:5984
	s_waitcnt lgkmcnt(1)
	v_mfma_f32_16x16x32_bf16 v[22:25], v[82:85], v[18:21], v[22:25]
	v_mfma_f32_16x16x32_bf16 v[26:29], v[50:53], v[18:21], v[26:29]
	v_mfma_f32_16x16x32_bf16 v[30:33], v[54:57], v[18:21], v[30:33]
	v_mfma_f32_16x16x32_bf16 v[34:37], v[58:61], v[18:21], v[34:37]
	v_mfma_f32_16x16x32_bf16 v[38:41], v[62:65], v[18:21], v[38:41]
	v_mfma_f32_16x16x32_bf16 v[42:45], v[66:69], v[18:21], v[42:45]
	v_mfma_f32_16x16x32_bf16 v[46:49], v[70:73], v[18:21], v[46:49]
	v_mfma_f32_16x16x32_bf16 v[14:17], v[74:77], v[18:21], v[14:17]
	ds_read_b128 v[18:21], v150 offset:1856
	ds_read_b128 v[74:77], v97 offset:6048
	s_waitcnt lgkmcnt(1)
	v_mfma_f32_16x16x32_bf16 v[22:25], v[78:81], v[18:21], v[22:25]
	v_mfma_f32_16x16x32_bf16 v[26:29], v[82:85], v[18:21], v[26:29]
	v_mfma_f32_16x16x32_bf16 v[30:33], v[50:53], v[18:21], v[30:33]
	v_mfma_f32_16x16x32_bf16 v[34:37], v[54:57], v[18:21], v[34:37]
	v_mfma_f32_16x16x32_bf16 v[38:41], v[58:61], v[18:21], v[38:41]
	v_mfma_f32_16x16x32_bf16 v[42:45], v[62:65], v[18:21], v[42:45]
	v_mfma_f32_16x16x32_bf16 v[46:49], v[66:69], v[18:21], v[46:49]
	v_mfma_f32_16x16x32_bf16 v[14:17], v[70:73], v[18:21], v[14:17]
	ds_read_b128 v[18:21], v150 offset:1920
	ds_read_b128 v[70:73], v97 offset:6112
	s_waitcnt lgkmcnt(1)
	v_mfma_f32_16x16x32_bf16 v[22:25], v[74:77], v[18:21], v[22:25]
	v_mfma_f32_16x16x32_bf16 v[26:29], v[78:81], v[18:21], v[26:29]
	v_mfma_f32_16x16x32_bf16 v[30:33], v[82:85], v[18:21], v[30:33]
	v_mfma_f32_16x16x32_bf16 v[34:37], v[50:53], v[18:21], v[34:37]
	v_mfma_f32_16x16x32_bf16 v[38:41], v[54:57], v[18:21], v[38:41]
	v_mfma_f32_16x16x32_bf16 v[42:45], v[58:61], v[18:21], v[42:45]
	v_mfma_f32_16x16x32_bf16 v[46:49], v[62:65], v[18:21], v[46:49]
	v_mfma_f32_16x16x32_bf16 v[14:17], v[66:69], v[18:21], v[14:17]
	ds_read_b128 v[18:21], v150 offset:1984
	ds_read_b128 v[66:69], v97 offset:6176
	s_waitcnt lgkmcnt(1)
	v_mfma_f32_16x16x32_bf16 v[22:25], v[70:73], v[18:21], v[22:25]
	v_mfma_f32_16x16x32_bf16 v[26:29], v[74:77], v[18:21], v[26:29]
	v_mfma_f32_16x16x32_bf16 v[30:33], v[78:81], v[18:21], v[30:33]
	v_mfma_f32_16x16x32_bf16 v[34:37], v[82:85], v[18:21], v[34:37]
	v_mfma_f32_16x16x32_bf16 v[38:41], v[50:53], v[18:21], v[38:41]
	v_mfma_f32_16x16x32_bf16 v[42:45], v[54:57], v[18:21], v[42:45]
	v_mfma_f32_16x16x32_bf16 v[46:49], v[58:61], v[18:21], v[46:49]
	v_mfma_f32_16x16x32_bf16 v[14:17], v[62:65], v[18:21], v[14:17]
	ds_read_b128 v[18:21], v150 offset:2048
	ds_read_b128 v[62:65], v97 offset:6240
	s_waitcnt lgkmcnt(1)
	v_mfma_f32_16x16x32_bf16 v[22:25], v[66:69], v[18:21], v[22:25]
	v_mfma_f32_16x16x32_bf16 v[26:29], v[70:73], v[18:21], v[26:29]
	v_mfma_f32_16x16x32_bf16 v[30:33], v[74:77], v[18:21], v[30:33]
	v_mfma_f32_16x16x32_bf16 v[34:37], v[78:81], v[18:21], v[34:37]
	v_mfma_f32_16x16x32_bf16 v[38:41], v[82:85], v[18:21], v[38:41]
	v_mfma_f32_16x16x32_bf16 v[42:45], v[50:53], v[18:21], v[42:45]
	v_mfma_f32_16x16x32_bf16 v[46:49], v[54:57], v[18:21], v[46:49]
	v_mfma_f32_16x16x32_bf16 v[14:17], v[58:61], v[18:21], v[14:17]
	ds_read_b128 v[18:21], v150 offset:2112
	ds_read_b128 v[58:61], v97 offset:6304
	s_waitcnt lgkmcnt(1)
	v_mfma_f32_16x16x32_bf16 v[22:25], v[62:65], v[18:21], v[22:25]
	v_mfma_f32_16x16x32_bf16 v[26:29], v[66:69], v[18:21], v[26:29]
	v_mfma_f32_16x16x32_bf16 v[30:33], v[70:73], v[18:21], v[30:33]
	v_mfma_f32_16x16x32_bf16 v[34:37], v[74:77], v[18:21], v[34:37]
	v_mfma_f32_16x16x32_bf16 v[38:41], v[78:81], v[18:21], v[38:41]
	v_mfma_f32_16x16x32_bf16 v[42:45], v[82:85], v[18:21], v[42:45]
	v_mfma_f32_16x16x32_bf16 v[46:49], v[50:53], v[18:21], v[46:49]
	v_mfma_f32_16x16x32_bf16 v[14:17], v[54:57], v[18:21], v[14:17]
	ds_read_b128 v[18:21], v150 offset:2176
	ds_read_b128 v[54:57], v97 offset:6368
	s_waitcnt lgkmcnt(1)
	v_mfma_f32_16x16x32_bf16 v[22:25], v[58:61], v[18:21], v[22:25]
	v_mfma_f32_16x16x32_bf16 v[26:29], v[62:65], v[18:21], v[26:29]
	v_mfma_f32_16x16x32_bf16 v[30:33], v[66:69], v[18:21], v[30:33]
	v_mfma_f32_16x16x32_bf16 v[34:37], v[70:73], v[18:21], v[34:37]
	v_mfma_f32_16x16x32_bf16 v[38:41], v[74:77], v[18:21], v[38:41]
	v_mfma_f32_16x16x32_bf16 v[42:45], v[78:81], v[18:21], v[42:45]
	v_mfma_f32_16x16x32_bf16 v[46:49], v[82:85], v[18:21], v[46:49]
	v_mfma_f32_16x16x32_bf16 v[14:17], v[50:53], v[18:21], v[14:17]
	ds_read_b128 v[18:21], v150 offset:2240
	ds_read_b128 v[50:53], v97 offset:6432
	s_waitcnt lgkmcnt(1)
	v_mfma_f32_16x16x32_bf16 v[22:25], v[54:57], v[18:21], v[22:25]
	v_mfma_f32_16x16x32_bf16 v[26:29], v[58:61], v[18:21], v[26:29]
	v_mfma_f32_16x16x32_bf16 v[30:33], v[62:65], v[18:21], v[30:33]
	v_mfma_f32_16x16x32_bf16 v[34:37], v[66:69], v[18:21], v[34:37]
	v_mfma_f32_16x16x32_bf16 v[38:41], v[70:73], v[18:21], v[38:41]
	v_mfma_f32_16x16x32_bf16 v[42:45], v[74:77], v[18:21], v[42:45]
	v_mfma_f32_16x16x32_bf16 v[46:49], v[78:81], v[18:21], v[46:49]
	v_mfma_f32_16x16x32_bf16 v[14:17], v[82:85], v[18:21], v[14:17]
	ds_read_b128 v[18:21], v150 offset:2304
	ds_read_b128 v[82:85], v97 offset:6496
	s_waitcnt lgkmcnt(1)
	v_mfma_f32_16x16x32_bf16 v[22:25], v[50:53], v[18:21], v[22:25]
	v_mfma_f32_16x16x32_bf16 v[26:29], v[54:57], v[18:21], v[26:29]
	v_mfma_f32_16x16x32_bf16 v[30:33], v[58:61], v[18:21], v[30:33]
	v_mfma_f32_16x16x32_bf16 v[34:37], v[62:65], v[18:21], v[34:37]
	v_mfma_f32_16x16x32_bf16 v[38:41], v[66:69], v[18:21], v[38:41]
	v_mfma_f32_16x16x32_bf16 v[42:45], v[70:73], v[18:21], v[42:45]
	v_mfma_f32_16x16x32_bf16 v[46:49], v[74:77], v[18:21], v[46:49]
	v_mfma_f32_16x16x32_bf16 v[14:17], v[78:81], v[18:21], v[14:17]
	ds_read_b128 v[18:21], v150 offset:2368
	ds_read_b128 v[78:81], v97 offset:6560
	s_waitcnt lgkmcnt(1)
	v_mfma_f32_16x16x32_bf16 v[22:25], v[82:85], v[18:21], v[22:25]
	v_mfma_f32_16x16x32_bf16 v[26:29], v[50:53], v[18:21], v[26:29]
	v_mfma_f32_16x16x32_bf16 v[30:33], v[54:57], v[18:21], v[30:33]
	v_mfma_f32_16x16x32_bf16 v[34:37], v[58:61], v[18:21], v[34:37]
	v_mfma_f32_16x16x32_bf16 v[38:41], v[62:65], v[18:21], v[38:41]
	v_mfma_f32_16x16x32_bf16 v[42:45], v[66:69], v[18:21], v[42:45]
	v_mfma_f32_16x16x32_bf16 v[46:49], v[70:73], v[18:21], v[46:49]
	v_mfma_f32_16x16x32_bf16 v[14:17], v[74:77], v[18:21], v[14:17]
	ds_read_b128 v[18:21], v150 offset:2432
	ds_read_b128 v[74:77], v97 offset:6624
	s_waitcnt lgkmcnt(1)
	v_mfma_f32_16x16x32_bf16 v[22:25], v[78:81], v[18:21], v[22:25]
	v_mfma_f32_16x16x32_bf16 v[26:29], v[82:85], v[18:21], v[26:29]
	v_mfma_f32_16x16x32_bf16 v[30:33], v[50:53], v[18:21], v[30:33]
	v_mfma_f32_16x16x32_bf16 v[34:37], v[54:57], v[18:21], v[34:37]
	v_mfma_f32_16x16x32_bf16 v[38:41], v[58:61], v[18:21], v[38:41]
	v_mfma_f32_16x16x32_bf16 v[42:45], v[62:65], v[18:21], v[42:45]
	v_mfma_f32_16x16x32_bf16 v[46:49], v[66:69], v[18:21], v[46:49]
	v_mfma_f32_16x16x32_bf16 v[14:17], v[70:73], v[18:21], v[14:17]
	ds_read_b128 v[18:21], v150 offset:2496
	ds_read_b128 v[70:73], v97 offset:6688
	s_waitcnt lgkmcnt(1)
	v_mfma_f32_16x16x32_bf16 v[22:25], v[74:77], v[18:21], v[22:25]
	v_mfma_f32_16x16x32_bf16 v[26:29], v[78:81], v[18:21], v[26:29]
	v_mfma_f32_16x16x32_bf16 v[30:33], v[82:85], v[18:21], v[30:33]
	v_mfma_f32_16x16x32_bf16 v[34:37], v[50:53], v[18:21], v[34:37]
	v_mfma_f32_16x16x32_bf16 v[38:41], v[54:57], v[18:21], v[38:41]
	v_mfma_f32_16x16x32_bf16 v[42:45], v[58:61], v[18:21], v[42:45]
	v_mfma_f32_16x16x32_bf16 v[46:49], v[62:65], v[18:21], v[46:49]
	v_mfma_f32_16x16x32_bf16 v[14:17], v[66:69], v[18:21], v[14:17]
	ds_read_b128 v[18:21], v150 offset:2560
	ds_read_b128 v[66:69], v97 offset:6752
	s_waitcnt lgkmcnt(1)
	v_mfma_f32_16x16x32_bf16 v[22:25], v[70:73], v[18:21], v[22:25]
	v_mfma_f32_16x16x32_bf16 v[26:29], v[74:77], v[18:21], v[26:29]
	v_mfma_f32_16x16x32_bf16 v[30:33], v[78:81], v[18:21], v[30:33]
	v_mfma_f32_16x16x32_bf16 v[34:37], v[82:85], v[18:21], v[34:37]
	v_mfma_f32_16x16x32_bf16 v[38:41], v[50:53], v[18:21], v[38:41]
	v_mfma_f32_16x16x32_bf16 v[42:45], v[54:57], v[18:21], v[42:45]
	v_mfma_f32_16x16x32_bf16 v[46:49], v[58:61], v[18:21], v[46:49]
	v_mfma_f32_16x16x32_bf16 v[14:17], v[62:65], v[18:21], v[14:17]
	ds_read_b128 v[18:21], v150 offset:2624
	ds_read_b128 v[62:65], v97 offset:6816
	s_waitcnt lgkmcnt(1)
	v_mfma_f32_16x16x32_bf16 v[22:25], v[66:69], v[18:21], v[22:25]
	v_mfma_f32_16x16x32_bf16 v[26:29], v[70:73], v[18:21], v[26:29]
	v_mfma_f32_16x16x32_bf16 v[30:33], v[74:77], v[18:21], v[30:33]
	v_mfma_f32_16x16x32_bf16 v[34:37], v[78:81], v[18:21], v[34:37]
	v_mfma_f32_16x16x32_bf16 v[38:41], v[82:85], v[18:21], v[38:41]
	v_mfma_f32_16x16x32_bf16 v[42:45], v[50:53], v[18:21], v[42:45]
	v_mfma_f32_16x16x32_bf16 v[46:49], v[54:57], v[18:21], v[46:49]
	v_mfma_f32_16x16x32_bf16 v[14:17], v[58:61], v[18:21], v[14:17]
	ds_read_b128 v[18:21], v150 offset:2688
	ds_read_b128 v[58:61], v97 offset:6880
	s_waitcnt lgkmcnt(1)
	v_mfma_f32_16x16x32_bf16 v[22:25], v[62:65], v[18:21], v[22:25]
	v_mfma_f32_16x16x32_bf16 v[26:29], v[66:69], v[18:21], v[26:29]
	v_mfma_f32_16x16x32_bf16 v[30:33], v[70:73], v[18:21], v[30:33]
	v_mfma_f32_16x16x32_bf16 v[34:37], v[74:77], v[18:21], v[34:37]
	v_mfma_f32_16x16x32_bf16 v[38:41], v[78:81], v[18:21], v[38:41]
	v_mfma_f32_16x16x32_bf16 v[42:45], v[82:85], v[18:21], v[42:45]
	v_mfma_f32_16x16x32_bf16 v[46:49], v[50:53], v[18:21], v[46:49]
	v_mfma_f32_16x16x32_bf16 v[14:17], v[54:57], v[18:21], v[14:17]
	ds_read_b128 v[18:21], v150 offset:2752
	ds_read_b128 v[54:57], v97 offset:6944
	s_waitcnt lgkmcnt(1)
	v_mfma_f32_16x16x32_bf16 v[22:25], v[58:61], v[18:21], v[22:25]
	v_mfma_f32_16x16x32_bf16 v[26:29], v[62:65], v[18:21], v[26:29]
	v_mfma_f32_16x16x32_bf16 v[30:33], v[66:69], v[18:21], v[30:33]
	v_mfma_f32_16x16x32_bf16 v[34:37], v[70:73], v[18:21], v[34:37]
	v_mfma_f32_16x16x32_bf16 v[38:41], v[74:77], v[18:21], v[38:41]
	v_mfma_f32_16x16x32_bf16 v[42:45], v[78:81], v[18:21], v[42:45]
	v_mfma_f32_16x16x32_bf16 v[46:49], v[82:85], v[18:21], v[46:49]
	v_mfma_f32_16x16x32_bf16 v[14:17], v[50:53], v[18:21], v[14:17]
	ds_read_b128 v[18:21], v150 offset:2816
	ds_read_b128 v[50:53], v97 offset:7008
	s_waitcnt lgkmcnt(1)
	v_mfma_f32_16x16x32_bf16 v[22:25], v[54:57], v[18:21], v[22:25]
	v_mfma_f32_16x16x32_bf16 v[26:29], v[58:61], v[18:21], v[26:29]
	v_mfma_f32_16x16x32_bf16 v[30:33], v[62:65], v[18:21], v[30:33]
	v_mfma_f32_16x16x32_bf16 v[34:37], v[66:69], v[18:21], v[34:37]
	v_mfma_f32_16x16x32_bf16 v[38:41], v[70:73], v[18:21], v[38:41]
	v_mfma_f32_16x16x32_bf16 v[42:45], v[74:77], v[18:21], v[42:45]
	v_mfma_f32_16x16x32_bf16 v[46:49], v[78:81], v[18:21], v[46:49]
	v_mfma_f32_16x16x32_bf16 v[14:17], v[82:85], v[18:21], v[14:17]
	ds_read_b128 v[18:21], v150 offset:2880
	ds_read_b128 v[82:85], v97 offset:7072
	s_waitcnt lgkmcnt(1)
	v_mfma_f32_16x16x32_bf16 v[22:25], v[50:53], v[18:21], v[22:25]
	v_mfma_f32_16x16x32_bf16 v[26:29], v[54:57], v[18:21], v[26:29]
	v_mfma_f32_16x16x32_bf16 v[30:33], v[58:61], v[18:21], v[30:33]
	v_mfma_f32_16x16x32_bf16 v[34:37], v[62:65], v[18:21], v[34:37]
	v_mfma_f32_16x16x32_bf16 v[38:41], v[66:69], v[18:21], v[38:41]
	v_mfma_f32_16x16x32_bf16 v[42:45], v[70:73], v[18:21], v[42:45]
	v_mfma_f32_16x16x32_bf16 v[46:49], v[74:77], v[18:21], v[46:49]
	v_mfma_f32_16x16x32_bf16 v[14:17], v[78:81], v[18:21], v[14:17]
	ds_read_b128 v[18:21], v150 offset:2944
	ds_read_b128 v[78:81], v97 offset:7136
	s_waitcnt lgkmcnt(1)
	v_mfma_f32_16x16x32_bf16 v[22:25], v[82:85], v[18:21], v[22:25]
	v_mfma_f32_16x16x32_bf16 v[26:29], v[50:53], v[18:21], v[26:29]
	v_mfma_f32_16x16x32_bf16 v[30:33], v[54:57], v[18:21], v[30:33]
	v_mfma_f32_16x16x32_bf16 v[34:37], v[58:61], v[18:21], v[34:37]
	v_mfma_f32_16x16x32_bf16 v[38:41], v[62:65], v[18:21], v[38:41]
	v_mfma_f32_16x16x32_bf16 v[42:45], v[66:69], v[18:21], v[42:45]
	v_mfma_f32_16x16x32_bf16 v[46:49], v[70:73], v[18:21], v[46:49]
	v_mfma_f32_16x16x32_bf16 v[14:17], v[74:77], v[18:21], v[14:17]
	ds_read_b128 v[18:21], v150 offset:3008
	ds_read_b128 v[74:77], v97 offset:7200
	s_waitcnt lgkmcnt(1)
	v_mfma_f32_16x16x32_bf16 v[22:25], v[78:81], v[18:21], v[22:25]
	v_mfma_f32_16x16x32_bf16 v[26:29], v[82:85], v[18:21], v[26:29]
	v_mfma_f32_16x16x32_bf16 v[30:33], v[50:53], v[18:21], v[30:33]
	v_mfma_f32_16x16x32_bf16 v[34:37], v[54:57], v[18:21], v[34:37]
	v_mfma_f32_16x16x32_bf16 v[38:41], v[58:61], v[18:21], v[38:41]
	v_mfma_f32_16x16x32_bf16 v[42:45], v[62:65], v[18:21], v[42:45]
	v_mfma_f32_16x16x32_bf16 v[46:49], v[66:69], v[18:21], v[46:49]
	v_mfma_f32_16x16x32_bf16 v[14:17], v[70:73], v[18:21], v[14:17]
	ds_read_b128 v[18:21], v150 offset:3072
	ds_read_b128 v[70:73], v97 offset:7264
	s_waitcnt lgkmcnt(1)
	v_mfma_f32_16x16x32_bf16 v[22:25], v[74:77], v[18:21], v[22:25]
	v_mfma_f32_16x16x32_bf16 v[26:29], v[78:81], v[18:21], v[26:29]
	v_mfma_f32_16x16x32_bf16 v[30:33], v[82:85], v[18:21], v[30:33]
	v_mfma_f32_16x16x32_bf16 v[34:37], v[50:53], v[18:21], v[34:37]
	v_mfma_f32_16x16x32_bf16 v[38:41], v[54:57], v[18:21], v[38:41]
	v_mfma_f32_16x16x32_bf16 v[42:45], v[58:61], v[18:21], v[42:45]
	v_mfma_f32_16x16x32_bf16 v[46:49], v[62:65], v[18:21], v[46:49]
	v_mfma_f32_16x16x32_bf16 v[14:17], v[66:69], v[18:21], v[14:17]
	ds_read_b128 v[18:21], v150 offset:3136
	ds_read_b128 v[66:69], v97 offset:7328
	s_waitcnt lgkmcnt(1)
	v_mfma_f32_16x16x32_bf16 v[22:25], v[70:73], v[18:21], v[22:25]
	v_mfma_f32_16x16x32_bf16 v[26:29], v[74:77], v[18:21], v[26:29]
	v_mfma_f32_16x16x32_bf16 v[30:33], v[78:81], v[18:21], v[30:33]
	v_mfma_f32_16x16x32_bf16 v[34:37], v[82:85], v[18:21], v[34:37]
	v_mfma_f32_16x16x32_bf16 v[38:41], v[50:53], v[18:21], v[38:41]
	v_mfma_f32_16x16x32_bf16 v[42:45], v[54:57], v[18:21], v[42:45]
	v_mfma_f32_16x16x32_bf16 v[46:49], v[58:61], v[18:21], v[46:49]
	v_mfma_f32_16x16x32_bf16 v[14:17], v[62:65], v[18:21], v[14:17]
	ds_read_b128 v[18:21], v150 offset:3200
	ds_read_b128 v[62:65], v97 offset:7392
	s_waitcnt lgkmcnt(1)
	v_mfma_f32_16x16x32_bf16 v[22:25], v[66:69], v[18:21], v[22:25]
	v_mfma_f32_16x16x32_bf16 v[26:29], v[70:73], v[18:21], v[26:29]
	v_mfma_f32_16x16x32_bf16 v[30:33], v[74:77], v[18:21], v[30:33]
	v_mfma_f32_16x16x32_bf16 v[34:37], v[78:81], v[18:21], v[34:37]
	v_mfma_f32_16x16x32_bf16 v[38:41], v[82:85], v[18:21], v[38:41]
	v_mfma_f32_16x16x32_bf16 v[42:45], v[50:53], v[18:21], v[42:45]
	v_mfma_f32_16x16x32_bf16 v[46:49], v[54:57], v[18:21], v[46:49]
	v_mfma_f32_16x16x32_bf16 v[14:17], v[58:61], v[18:21], v[14:17]
	ds_read_b128 v[18:21], v150 offset:3264
	ds_read_b128 v[58:61], v97 offset:7456
	s_waitcnt lgkmcnt(1)
	v_mfma_f32_16x16x32_bf16 v[22:25], v[62:65], v[18:21], v[22:25]
	v_mfma_f32_16x16x32_bf16 v[26:29], v[66:69], v[18:21], v[26:29]
	v_mfma_f32_16x16x32_bf16 v[30:33], v[70:73], v[18:21], v[30:33]
	v_mfma_f32_16x16x32_bf16 v[34:37], v[74:77], v[18:21], v[34:37]
	v_mfma_f32_16x16x32_bf16 v[38:41], v[78:81], v[18:21], v[38:41]
	v_mfma_f32_16x16x32_bf16 v[42:45], v[82:85], v[18:21], v[42:45]
	v_mfma_f32_16x16x32_bf16 v[46:49], v[50:53], v[18:21], v[46:49]
	v_mfma_f32_16x16x32_bf16 v[14:17], v[54:57], v[18:21], v[14:17]
	ds_read_b128 v[18:21], v150 offset:3328
	ds_read_b128 v[54:57], v97 offset:7520
	s_waitcnt lgkmcnt(1)
	v_mfma_f32_16x16x32_bf16 v[22:25], v[58:61], v[18:21], v[22:25]
	v_mfma_f32_16x16x32_bf16 v[26:29], v[62:65], v[18:21], v[26:29]
	v_mfma_f32_16x16x32_bf16 v[30:33], v[66:69], v[18:21], v[30:33]
	v_mfma_f32_16x16x32_bf16 v[34:37], v[70:73], v[18:21], v[34:37]
	v_mfma_f32_16x16x32_bf16 v[38:41], v[74:77], v[18:21], v[38:41]
	v_mfma_f32_16x16x32_bf16 v[42:45], v[78:81], v[18:21], v[42:45]
	v_mfma_f32_16x16x32_bf16 v[46:49], v[82:85], v[18:21], v[46:49]
	v_mfma_f32_16x16x32_bf16 v[14:17], v[50:53], v[18:21], v[14:17]
	ds_read_b128 v[18:21], v150 offset:3392
	ds_read_b128 v[50:53], v97 offset:7584
	s_waitcnt lgkmcnt(1)
	v_mfma_f32_16x16x32_bf16 v[22:25], v[54:57], v[18:21], v[22:25]
	v_mfma_f32_16x16x32_bf16 v[26:29], v[58:61], v[18:21], v[26:29]
	v_mfma_f32_16x16x32_bf16 v[30:33], v[62:65], v[18:21], v[30:33]
	v_mfma_f32_16x16x32_bf16 v[34:37], v[66:69], v[18:21], v[34:37]
	v_mfma_f32_16x16x32_bf16 v[38:41], v[70:73], v[18:21], v[38:41]
	v_mfma_f32_16x16x32_bf16 v[42:45], v[74:77], v[18:21], v[42:45]
	v_mfma_f32_16x16x32_bf16 v[46:49], v[78:81], v[18:21], v[46:49]
	v_mfma_f32_16x16x32_bf16 v[14:17], v[82:85], v[18:21], v[14:17]
	ds_read_b128 v[18:21], v150 offset:3456
	ds_read_b128 v[82:85], v97 offset:7648
	s_waitcnt lgkmcnt(1)
	v_mfma_f32_16x16x32_bf16 v[22:25], v[50:53], v[18:21], v[22:25]
	v_mfma_f32_16x16x32_bf16 v[26:29], v[54:57], v[18:21], v[26:29]
	v_mfma_f32_16x16x32_bf16 v[30:33], v[58:61], v[18:21], v[30:33]
	v_mfma_f32_16x16x32_bf16 v[34:37], v[62:65], v[18:21], v[34:37]
	v_mfma_f32_16x16x32_bf16 v[38:41], v[66:69], v[18:21], v[38:41]
	v_mfma_f32_16x16x32_bf16 v[42:45], v[70:73], v[18:21], v[42:45]
	v_mfma_f32_16x16x32_bf16 v[46:49], v[74:77], v[18:21], v[46:49]
	v_mfma_f32_16x16x32_bf16 v[14:17], v[78:81], v[18:21], v[14:17]
	ds_read_b128 v[18:21], v150 offset:3520
	ds_read_b128 v[78:81], v97 offset:7712
	s_waitcnt lgkmcnt(1)
	v_mfma_f32_16x16x32_bf16 v[22:25], v[82:85], v[18:21], v[22:25]
	v_mfma_f32_16x16x32_bf16 v[26:29], v[50:53], v[18:21], v[26:29]
	v_mfma_f32_16x16x32_bf16 v[30:33], v[54:57], v[18:21], v[30:33]
	v_mfma_f32_16x16x32_bf16 v[34:37], v[58:61], v[18:21], v[34:37]
	v_mfma_f32_16x16x32_bf16 v[38:41], v[62:65], v[18:21], v[38:41]
	v_mfma_f32_16x16x32_bf16 v[42:45], v[66:69], v[18:21], v[42:45]
	v_mfma_f32_16x16x32_bf16 v[46:49], v[70:73], v[18:21], v[46:49]
	v_mfma_f32_16x16x32_bf16 v[14:17], v[74:77], v[18:21], v[14:17]
	ds_read_b128 v[18:21], v150 offset:3584
	ds_read_b128 v[74:77], v97 offset:7776
	s_waitcnt lgkmcnt(1)
	v_mfma_f32_16x16x32_bf16 v[22:25], v[78:81], v[18:21], v[22:25]
	v_mfma_f32_16x16x32_bf16 v[26:29], v[82:85], v[18:21], v[26:29]
	v_mfma_f32_16x16x32_bf16 v[30:33], v[50:53], v[18:21], v[30:33]
	v_mfma_f32_16x16x32_bf16 v[34:37], v[54:57], v[18:21], v[34:37]
	v_mfma_f32_16x16x32_bf16 v[38:41], v[58:61], v[18:21], v[38:41]
	v_mfma_f32_16x16x32_bf16 v[42:45], v[62:65], v[18:21], v[42:45]
	v_mfma_f32_16x16x32_bf16 v[46:49], v[66:69], v[18:21], v[46:49]
	v_mfma_f32_16x16x32_bf16 v[14:17], v[70:73], v[18:21], v[14:17]
	ds_read_b128 v[18:21], v150 offset:3648
	ds_read_b128 v[70:73], v97 offset:7840
	s_waitcnt lgkmcnt(1)
	v_mfma_f32_16x16x32_bf16 v[22:25], v[74:77], v[18:21], v[22:25]
	v_mfma_f32_16x16x32_bf16 v[26:29], v[78:81], v[18:21], v[26:29]
	v_mfma_f32_16x16x32_bf16 v[30:33], v[82:85], v[18:21], v[30:33]
	v_mfma_f32_16x16x32_bf16 v[34:37], v[50:53], v[18:21], v[34:37]
	v_mfma_f32_16x16x32_bf16 v[38:41], v[54:57], v[18:21], v[38:41]
	v_mfma_f32_16x16x32_bf16 v[42:45], v[58:61], v[18:21], v[42:45]
	v_mfma_f32_16x16x32_bf16 v[46:49], v[62:65], v[18:21], v[46:49]
	v_mfma_f32_16x16x32_bf16 v[18:21], v[66:69], v[18:21], v[14:17]
	ds_read_b128 v[66:69], v150 offset:3712
	s_nop 1
	ds_read_b128 v[14:17], v97 offset:7904
	s_waitcnt lgkmcnt(1)
	v_mfma_f32_16x16x32_bf16 v[22:25], v[70:73], v[66:69], v[22:25]
	v_mfma_f32_16x16x32_bf16 v[26:29], v[74:77], v[66:69], v[26:29]
	v_mfma_f32_16x16x32_bf16 v[30:33], v[78:81], v[66:69], v[30:33]
	v_mfma_f32_16x16x32_bf16 v[34:37], v[82:85], v[66:69], v[34:37]
	v_mfma_f32_16x16x32_bf16 v[38:41], v[50:53], v[66:69], v[38:41]
	v_mfma_f32_16x16x32_bf16 v[42:45], v[54:57], v[66:69], v[42:45]
	v_mfma_f32_16x16x32_bf16 v[46:49], v[58:61], v[66:69], v[46:49]
	v_mfma_f32_16x16x32_bf16 v[62:65], v[62:65], v[66:69], v[18:21]
	ds_read_b128 v[66:69], v150 offset:3776
	s_nop 1
	ds_read_b128 v[18:21], v97 offset:7968
	s_waitcnt lgkmcnt(1)
	v_mfma_f32_16x16x32_bf16 v[58:61], v[58:61], v[66:69], v[62:65]
	s_nop 2
	ds_read_b128 v[62:65], v150 offset:3840
	v_mfma_f32_16x16x32_bf16 v[22:25], v[14:17], v[66:69], v[22:25]
	v_mfma_f32_16x16x32_bf16 v[26:29], v[70:73], v[66:69], v[26:29]
	v_mfma_f32_16x16x32_bf16 v[30:33], v[74:77], v[66:69], v[30:33]
	v_mfma_f32_16x16x32_bf16 v[34:37], v[78:81], v[66:69], v[34:37]
	v_mfma_f32_16x16x32_bf16 v[38:41], v[82:85], v[66:69], v[38:41]
	v_mfma_f32_16x16x32_bf16 v[42:45], v[50:53], v[66:69], v[42:45]
	v_mfma_f32_16x16x32_bf16 v[46:49], v[54:57], v[66:69], v[46:49]
	s_waitcnt lgkmcnt(0)
	v_mfma_f32_16x16x32_bf16 v[66:69], v[18:21], v[62:65], v[22:25]
	s_nop 2
	ds_read_b128 v[22:25], v97 offset:8032
	v_mfma_f32_16x16x32_bf16 v[54:57], v[54:57], v[62:65], v[58:61]
	s_nop 2
	ds_read_b128 v[58:61], v150 offset:3904
	v_mfma_f32_16x16x32_bf16 v[26:29], v[14:17], v[62:65], v[26:29]
	v_mfma_f32_16x16x32_bf16 v[30:33], v[70:73], v[62:65], v[30:33]
	v_mfma_f32_16x16x32_bf16 v[34:37], v[74:77], v[62:65], v[34:37]
	v_mfma_f32_16x16x32_bf16 v[38:41], v[78:81], v[62:65], v[38:41]
	v_mfma_f32_16x16x32_bf16 v[42:45], v[82:85], v[62:65], v[42:45]
	v_mfma_f32_16x16x32_bf16 v[46:49], v[50:53], v[62:65], v[46:49]
	s_waitcnt lgkmcnt(0)
	v_mfma_f32_16x16x32_bf16 v[62:65], v[22:25], v[58:61], v[66:69]
	v_mfma_f32_16x16x32_bf16 v[66:69], v[18:21], v[58:61], v[26:29]
	s_nop 2
	ds_read_b128 v[26:29], v97 offset:8096
	v_mfma_f32_16x16x32_bf16 v[50:53], v[50:53], v[58:61], v[54:57]
	s_nop 2
	ds_read_b128 v[54:57], v150 offset:3968
	v_mfma_f32_16x16x32_bf16 v[30:33], v[14:17], v[58:61], v[30:33]
	v_mfma_f32_16x16x32_bf16 v[34:37], v[70:73], v[58:61], v[34:37]
	v_mfma_f32_16x16x32_bf16 v[38:41], v[74:77], v[58:61], v[38:41]
	v_mfma_f32_16x16x32_bf16 v[42:45], v[78:81], v[58:61], v[42:45]
	v_mfma_f32_16x16x32_bf16 v[46:49], v[82:85], v[58:61], v[46:49]
	s_waitcnt lgkmcnt(0)
	v_mfma_f32_16x16x32_bf16 v[58:61], v[26:29], v[54:57], v[62:65]
	v_mfma_f32_16x16x32_bf16 v[62:65], v[22:25], v[54:57], v[66:69]
	v_mfma_f32_16x16x32_bf16 v[66:69], v[18:21], v[54:57], v[30:33]
	v_mfma_f32_16x16x32_bf16 v[34:37], v[14:17], v[54:57], v[34:37]
	s_nop 1
	ds_read_b128 v[30:33], v97 offset:8160
	v_mfma_f32_16x16x32_bf16 v[38:41], v[70:73], v[54:57], v[38:41]
	v_mfma_f32_16x16x32_bf16 v[42:45], v[74:77], v[54:57], v[42:45]
	v_mfma_f32_16x16x32_bf16 v[46:49], v[78:81], v[54:57], v[46:49]
	v_mfma_f32_16x16x32_bf16 v[50:53], v[82:85], v[54:57], v[50:53]
	ds_read_b128 v[54:57], v150 offset:4032
	s_waitcnt lgkmcnt(0)
	v_mfma_f32_16x16x32_bf16 v[82:85], v[70:73], v[54:57], v[42:45]
	s_nop 2
	ds_read_b128 v[42:45], v97 offset:8224
	v_mfma_f32_16x16x32_bf16 v[50:53], v[78:81], v[54:57], v[50:53]
	ds_read_b128 v[78:81], v150 offset:4096
	v_mfma_f32_16x16x32_bf16 v[58:61], v[30:33], v[54:57], v[58:61]
	v_mfma_f32_16x16x32_bf16 v[62:65], v[26:29], v[54:57], v[62:65]
	v_mfma_f32_16x16x32_bf16 v[66:69], v[22:25], v[54:57], v[66:69]
	v_mfma_f32_16x16x32_bf16 v[34:37], v[18:21], v[54:57], v[34:37]
	v_mfma_f32_16x16x32_bf16 v[38:41], v[14:17], v[54:57], v[38:41]
	v_mfma_f32_16x16x32_bf16 v[46:49], v[74:77], v[54:57], v[46:49]
	ds_read_b128 v[54:57], v97 offset:8288
	s_waitcnt lgkmcnt(1)
	v_mfma_f32_16x16x32_bf16 v[58:61], v[42:45], v[78:81], v[58:61]
	v_mfma_f32_16x16x32_bf16 v[140:143], v[30:33], v[78:81], v[62:65]
	v_mfma_f32_16x16x32_bf16 v[144:147], v[26:29], v[78:81], v[66:69]
	v_mfma_f32_16x16x32_bf16 v[34:37], v[22:25], v[78:81], v[34:37]
	v_mfma_f32_16x16x32_bf16 v[38:41], v[18:21], v[78:81], v[38:41]
	v_mfma_f32_16x16x32_bf16 v[82:85], v[14:17], v[78:81], v[82:85]
	v_mfma_f32_16x16x32_bf16 v[190:193], v[70:73], v[78:81], v[46:49]
	v_mfma_f32_16x16x32_bf16 v[74:77], v[74:77], v[78:81], v[50:53]
	ds_read_b128 v[78:81], v150 offset:4160
	s_waitcnt lgkmcnt(0)
	v_mfma_f32_16x16x32_bf16 v[70:73], v[70:73], v[78:81], v[74:77]
	s_nop 4
	ds_read_b128 v[74:77], v150 offset:4224
	v_mfma_f32_16x16x32_bf16 v[50:53], v[26:29], v[78:81], v[34:37]
	v_mfma_f32_16x16x32_bf16 v[46:49], v[22:25], v[78:81], v[38:41]
	v_mfma_f32_16x16x32_bf16 v[38:41], v[18:21], v[78:81], v[82:85]
	s_nop 2
	ds_read_b128 v[82:85], v97 offset:8352
	v_mfma_f32_16x16x32_bf16 v[62:65], v[54:57], v[78:81], v[58:61]
	v_mfma_f32_16x16x32_bf16 v[58:61], v[30:33], v[78:81], v[144:147]
	s_waitcnt lgkmcnt(1)
	v_mfma_f32_16x16x32_bf16 v[30:33], v[30:33], v[74:77], v[50:53]
	s_nop 0
	v_mov_b32_e32 v147, 0
	s_nop 0
	v_lshl_add_u64 v[50:51], s[42:43], 0, v[134:135]
	v_mfma_f32_16x16x32_bf16 v[26:29], v[26:29], v[74:77], v[46:49]
	v_mov_b32_e32 v135, 0
	s_nop 1
	v_lshl_add_u64 v[46:47], v[98:99], 1, v[50:51]
	v_add_co_u32_e32 v48, vcc, 0x4000, v46
	v_mfma_f32_16x16x32_bf16 v[66:69], v[42:45], v[78:81], v[140:143]
	s_nop 0
	v_addc_co_u32_e32 v49, vcc, 0, v47, vcc
	global_load_dwordx2 v[144:145], v[48:49], off
	v_mfma_f32_16x16x32_bf16 v[34:37], v[14:17], v[78:81], v[190:193]
	s_waitcnt lgkmcnt(0)
	v_mfma_f32_16x16x32_bf16 v[62:65], v[82:85], v[74:77], v[62:65]
	v_mfma_f32_16x16x32_bf16 v[54:57], v[54:57], v[74:77], v[66:69]
	v_mfma_f32_16x16x32_bf16 v[42:45], v[42:45], v[74:77], v[58:61]
	v_mfma_f32_16x16x32_bf16 v[22:25], v[22:25], v[74:77], v[38:41]
	v_mfma_f32_16x16x32_bf16 v[18:21], v[18:21], v[74:77], v[34:37]
	v_mfma_f32_16x16x32_bf16 v[14:17], v[14:17], v[74:77], v[70:73]
	s_nop 1
	v_lshl_add_u64 v[34:35], v[46:47], 0, s[16:17]
	s_mov_b64 s[4:5], exec
	v_readlane_b32 s6, v255, 37
	v_readlane_b32 s7, v255, 38
	s_and_b64 s[6:7], s[4:5], s[6:7]
	s_mov_b64 exec, s[6:7]
	s_cbranch_execz .LBB0_868
	global_load_short_d16_hi v147, v[34:35], off offset:-2
